# RWKV scan inner loop hand-written: fewer instructions, y-reduction pipelined into next step, operand reloads 2 steps ahead
# speedup vs baseline: 1.0007x; 1.0007x over previous
; #define LAS __attribute__((address_space(3)))
; __device__ __forceinline__ void scan_unit(ArgsK& a, LAS unsigned char* lds, int u, int tid, int wave, int lane) {
;     ...
;         if (scanw) {
;             LAS float* Bc = L0 + (c & 1) * SC_SET;
;             ScanOps oA, oB; f32x2 vA2, vB2;
;             SCAN_LD(oA, vA2, Bc, 0);
;             for (int tt = 0; tt < nt; tt += 2) {
;                 SCAN_LD(oB, vB2, Bc, tt + 1);
;                 SCAN_STEP(oA, vA2, Bc, tt);
;                 { const int tn = (tt + 2 < nt) ? tt + 2 : tt; SCAN_LD(oA, vA2, Bc, tn); }
;                 SCAN_STEP(oB, vB2, Bc, tt + 1);
;             }
.LBB0_219:
	s_and_b64 vcc, exec, s[4:5]
	s_cbranch_vccz .LBB0_204
	s_sub_i32 s5, s18, s24
	s_cmp_lt_i32 s5, 1
	s_cbranch_scc1 .LBB0_205
	s_bitcmp1_b32 s17, 0
	s_cselect_b32 s7, 0xe000, 0
	v_lshl_add_u32 v132, v136, 2, s7
	s_add_i32 s4, s7, 0x6000
	v_lshl_add_u32 v133, v161, 2, s4
	v_mov_b32_e32 v134, 0x1c000
	v_mov_b32_e32 v130, 0
	v_mov_b32_e32 v131, 0
	s_min_i32 s5, s5, 32
	ds_read_b128 v[20:23], v132 offset:32768
	ds_read_b128 v[24:27], v132 offset:32784
	ds_read_b128 v[44:47], v132 offset:16384
	ds_read_b128 v[48:51], v132 offset:16400
	ds_read_b64 v[60:61], v133 offset:0
	ds_read_b128 v[28:31], v132 offset:8192
	ds_read_b128 v[32:35], v132 offset:8208
	ds_read_b128 v[36:39], v132 offset:40960
	ds_read_b128 v[40:43], v132 offset:40976
	ds_read_b128 v[52:55], v132 offset:0
	ds_read_b128 v[56:59], v132 offset:16
	s_waitcnt lgkmcnt(0)
	ds_read_b128 v[62:65], v132 offset:33024
	ds_read_b128 v[66:69], v132 offset:33040
	ds_read_b128 v[86:89], v132 offset:16640
	ds_read_b128 v[90:93], v132 offset:16656
	ds_read_b64 v[102:103], v133 offset:256
	ds_read_b128 v[70:73], v132 offset:8448
	ds_read_b128 v[74:77], v132 offset:8464
	ds_read_b128 v[78:81], v132 offset:41216
	ds_read_b128 v[82:85], v132 offset:41232
	ds_read_b128 v[94:97], v132 offset:256
	ds_read_b128 v[98:101], v132 offset:272
	s_mov_b32 s6, 0
.Lscan4_loop:
	s_waitcnt lgkmcnt(12)
	v_pk_mul_f32 v[104:105], v[12:13], v[20:21]
	v_pk_mul_f32 v[106:107], v[4:5], v[20:21]
	v_add_f32_dpp v130, v130, v130 quad_perm:[1,0,3,2] row_mask:0xf bank_mask:0xf bound_ctrl:1
	v_add_f32_dpp v131, v131, v131 quad_perm:[1,0,3,2] row_mask:0xf bank_mask:0xf bound_ctrl:1
	v_pk_mul_f32 v[110:111], v[44:45], v[60:61] op_sel_hi:[1,0]
	v_pk_mul_f32 v[118:119], v[44:45], v[60:61] op_sel:[0,1]
	v_pk_fma_f32 v[104:105], v[14:15], v[22:23], v[104:105]
	v_pk_fma_f32 v[106:107], v[6:7], v[22:23], v[106:107]
	v_add_f32_dpp v130, v130, v130 quad_perm:[2,3,0,1] row_mask:0xf bank_mask:0xf bound_ctrl:1
	v_add_f32_dpp v131, v131, v131 quad_perm:[2,3,0,1] row_mask:0xf bank_mask:0xf bound_ctrl:1
	v_pk_mul_f32 v[112:113], v[46:47], v[60:61] op_sel_hi:[1,0]
	v_pk_mul_f32 v[120:121], v[46:47], v[60:61] op_sel:[0,1]
	v_pk_fma_f32 v[104:105], v[16:17], v[24:25], v[104:105]
	v_pk_fma_f32 v[106:107], v[8:9], v[24:25], v[106:107]
	v_add_f32_dpp v130, v130, v130 row_half_mirror row_mask:0xf bank_mask:0xf bound_ctrl:1
	v_add_f32_dpp v131, v131, v131 row_half_mirror row_mask:0xf bank_mask:0xf bound_ctrl:1
	v_pk_mul_f32 v[114:115], v[48:49], v[60:61] op_sel_hi:[1,0]
	v_pk_mul_f32 v[122:123], v[48:49], v[60:61] op_sel:[0,1]
	v_pk_fma_f32 v[104:105], v[18:19], v[26:27], v[104:105]
	v_pk_fma_f32 v[106:107], v[10:11], v[26:27], v[106:107]
	ds_write_b64 v134, v[130:131]
	v_pk_mul_f32 v[116:117], v[50:51], v[60:61] op_sel_hi:[1,0]
	v_pk_mul_f32 v[124:125], v[50:51], v[60:61] op_sel:[0,1]
	ds_read_b128 v[20:23], v132 offset:33280
	ds_read_b128 v[24:27], v132 offset:33296
	ds_read_b128 v[44:47], v132 offset:16896
	ds_read_b128 v[48:51], v132 offset:16912
	ds_read_b64 v[60:61], v133 offset:512
	v_add_f32_e32 v108, v104, v105
	v_add_f32_e32 v109, v106, v107
	v_pk_fma_f32 v[110:111], v[12:13], v[28:29], v[110:111]
	v_pk_fma_f32 v[118:119], v[4:5], v[28:29], v[118:119]
	v_add_f32_dpp v108, v108, v108 quad_perm:[1,0,3,2] row_mask:0xf bank_mask:0xf bound_ctrl:1
	v_add_f32_dpp v109, v109, v109 quad_perm:[1,0,3,2] row_mask:0xf bank_mask:0xf bound_ctrl:1
	v_pk_fma_f32 v[112:113], v[14:15], v[30:31], v[112:113]
	v_pk_fma_f32 v[120:121], v[6:7], v[30:31], v[120:121]
	v_add_f32_dpp v108, v108, v108 quad_perm:[2,3,0,1] row_mask:0xf bank_mask:0xf bound_ctrl:1
	v_add_f32_dpp v109, v109, v109 quad_perm:[2,3,0,1] row_mask:0xf bank_mask:0xf bound_ctrl:1
	v_pk_fma_f32 v[114:115], v[16:17], v[32:33], v[114:115]
	v_pk_fma_f32 v[122:123], v[8:9], v[32:33], v[122:123]
	v_add_f32_dpp v108, v108, v108 row_half_mirror row_mask:0xf bank_mask:0xf bound_ctrl:1
	v_add_f32_dpp v109, v109, v109 row_half_mirror row_mask:0xf bank_mask:0xf bound_ctrl:1
	v_pk_fma_f32 v[116:117], v[18:19], v[34:35], v[116:117]
	v_pk_fma_f32 v[124:125], v[10:11], v[34:35], v[124:125]
	ds_read_b128 v[28:31], v132 offset:8704
	ds_read_b128 v[32:35], v132 offset:8720
	v_pk_fma_f32 v[12:13], v[36:37], v[108:109], v[110:111] op_sel_hi:[1,0,1]
	v_pk_fma_f32 v[4:5], v[36:37], v[108:109], v[118:119] op_sel:[0,1,0]
	v_pk_fma_f32 v[14:15], v[38:39], v[108:109], v[112:113] op_sel_hi:[1,0,1]
	v_pk_fma_f32 v[6:7], v[38:39], v[108:109], v[120:121] op_sel:[0,1,0]
	v_pk_fma_f32 v[16:17], v[40:41], v[108:109], v[114:115] op_sel_hi:[1,0,1]
	v_pk_fma_f32 v[8:9], v[40:41], v[108:109], v[122:123] op_sel:[0,1,0]
	v_pk_fma_f32 v[18:19], v[42:43], v[108:109], v[116:117] op_sel_hi:[1,0,1]
	v_pk_fma_f32 v[10:11], v[42:43], v[108:109], v[124:125] op_sel:[0,1,0]
	ds_read_b128 v[36:39], v132 offset:41472
	ds_read_b128 v[40:43], v132 offset:41488
	v_pk_mul_f32 v[126:127], v[12:13], v[52:53]
	v_pk_mul_f32 v[128:129], v[4:5], v[52:53]
	v_pk_fma_f32 v[126:127], v[14:15], v[54:55], v[126:127]
	v_pk_fma_f32 v[128:129], v[6:7], v[54:55], v[128:129]
	v_pk_fma_f32 v[126:127], v[16:17], v[56:57], v[126:127]
	v_pk_fma_f32 v[128:129], v[8:9], v[56:57], v[128:129]
	v_pk_fma_f32 v[126:127], v[18:19], v[58:59], v[126:127]
	v_pk_fma_f32 v[128:129], v[10:11], v[58:59], v[128:129]
	ds_read_b128 v[52:55], v132 offset:512
	ds_read_b128 v[56:59], v132 offset:528
	v_add_f32_e32 v130, v126, v127
	v_add_f32_e32 v131, v128, v129
	s_waitcnt lgkmcnt(12)
; __device__ __forceinline__ void scan_unit(ArgsK& a, LAS unsigned char* lds, int u, int tid, int wave, int lane) {
;     ...
;             for (int tt = 0; tt < nt; tt += 2) {
;                 SCAN_LD(oB, vB2, Bc, tt + 1);
;                 SCAN_STEP(oA, vA2, Bc, tt);
;                 { const int tn = (tt + 2 < nt) ? tt + 2 : tt; SCAN_LD(oA, vA2, Bc, tn); }
;                 SCAN_STEP(oB, vB2, Bc, tt + 1);
;             }
	v_pk_mul_f32 v[104:105], v[12:13], v[62:63]
	v_pk_mul_f32 v[106:107], v[4:5], v[62:63]
	v_add_f32_dpp v130, v130, v130 quad_perm:[1,0,3,2] row_mask:0xf bank_mask:0xf bound_ctrl:1
	v_add_f32_dpp v131, v131, v131 quad_perm:[1,0,3,2] row_mask:0xf bank_mask:0xf bound_ctrl:1
	v_pk_mul_f32 v[110:111], v[86:87], v[102:103] op_sel_hi:[1,0]
	v_pk_mul_f32 v[118:119], v[86:87], v[102:103] op_sel:[0,1]
	v_pk_fma_f32 v[104:105], v[14:15], v[64:65], v[104:105]
	v_pk_fma_f32 v[106:107], v[6:7], v[64:65], v[106:107]
	v_add_f32_dpp v130, v130, v130 quad_perm:[2,3,0,1] row_mask:0xf bank_mask:0xf bound_ctrl:1
	v_add_f32_dpp v131, v131, v131 quad_perm:[2,3,0,1] row_mask:0xf bank_mask:0xf bound_ctrl:1
	v_pk_mul_f32 v[112:113], v[88:89], v[102:103] op_sel_hi:[1,0]
	v_pk_mul_f32 v[120:121], v[88:89], v[102:103] op_sel:[0,1]
	v_pk_fma_f32 v[104:105], v[16:17], v[66:67], v[104:105]
	v_pk_fma_f32 v[106:107], v[8:9], v[66:67], v[106:107]
	v_add_f32_dpp v130, v130, v130 row_half_mirror row_mask:0xf bank_mask:0xf bound_ctrl:1
	v_add_f32_dpp v131, v131, v131 row_half_mirror row_mask:0xf bank_mask:0xf bound_ctrl:1
	v_pk_mul_f32 v[114:115], v[90:91], v[102:103] op_sel_hi:[1,0]
	v_pk_mul_f32 v[122:123], v[90:91], v[102:103] op_sel:[0,1]
	v_pk_fma_f32 v[104:105], v[18:19], v[68:69], v[104:105]
	v_pk_fma_f32 v[106:107], v[10:11], v[68:69], v[106:107]
	ds_write_b64 v133, v[130:131] offset:24576
	v_pk_mul_f32 v[116:117], v[92:93], v[102:103] op_sel_hi:[1,0]
	v_pk_mul_f32 v[124:125], v[92:93], v[102:103] op_sel:[0,1]
	ds_read_b128 v[62:65], v132 offset:33536
	ds_read_b128 v[66:69], v132 offset:33552
	ds_read_b128 v[86:89], v132 offset:17152
	ds_read_b128 v[90:93], v132 offset:17168
	ds_read_b64 v[102:103], v133 offset:768
	v_add_f32_e32 v108, v104, v105
	v_add_f32_e32 v109, v106, v107
	v_pk_fma_f32 v[110:111], v[12:13], v[70:71], v[110:111]
	v_pk_fma_f32 v[118:119], v[4:5], v[70:71], v[118:119]
	v_add_f32_dpp v108, v108, v108 quad_perm:[1,0,3,2] row_mask:0xf bank_mask:0xf bound_ctrl:1
	v_add_f32_dpp v109, v109, v109 quad_perm:[1,0,3,2] row_mask:0xf bank_mask:0xf bound_ctrl:1
	v_pk_fma_f32 v[112:113], v[14:15], v[72:73], v[112:113]
	v_pk_fma_f32 v[120:121], v[6:7], v[72:73], v[120:121]
	v_add_f32_dpp v108, v108, v108 quad_perm:[2,3,0,1] row_mask:0xf bank_mask:0xf bound_ctrl:1
	v_add_f32_dpp v109, v109, v109 quad_perm:[2,3,0,1] row_mask:0xf bank_mask:0xf bound_ctrl:1
	v_pk_fma_f32 v[114:115], v[16:17], v[74:75], v[114:115]
	v_pk_fma_f32 v[122:123], v[8:9], v[74:75], v[122:123]
	v_add_f32_dpp v108, v108, v108 row_half_mirror row_mask:0xf bank_mask:0xf bound_ctrl:1
	v_add_f32_dpp v109, v109, v109 row_half_mirror row_mask:0xf bank_mask:0xf bound_ctrl:1
	v_pk_fma_f32 v[116:117], v[18:19], v[76:77], v[116:117]
	v_pk_fma_f32 v[124:125], v[10:11], v[76:77], v[124:125]
	ds_read_b128 v[70:73], v132 offset:8960
	ds_read_b128 v[74:77], v132 offset:8976
	v_pk_fma_f32 v[12:13], v[78:79], v[108:109], v[110:111] op_sel_hi:[1,0,1]
	v_pk_fma_f32 v[4:5], v[78:79], v[108:109], v[118:119] op_sel:[0,1,0]
	v_pk_fma_f32 v[14:15], v[80:81], v[108:109], v[112:113] op_sel_hi:[1,0,1]
	v_pk_fma_f32 v[6:7], v[80:81], v[108:109], v[120:121] op_sel:[0,1,0]
	v_pk_fma_f32 v[16:17], v[82:83], v[108:109], v[114:115] op_sel_hi:[1,0,1]
	v_pk_fma_f32 v[8:9], v[82:83], v[108:109], v[122:123] op_sel:[0,1,0]
	v_pk_fma_f32 v[18:19], v[84:85], v[108:109], v[116:117] op_sel_hi:[1,0,1]
	v_pk_fma_f32 v[10:11], v[84:85], v[108:109], v[124:125] op_sel:[0,1,0]
	ds_read_b128 v[78:81], v132 offset:41728
	ds_read_b128 v[82:85], v132 offset:41744
	v_pk_mul_f32 v[126:127], v[12:13], v[94:95]
	v_pk_mul_f32 v[128:129], v[4:5], v[94:95]
	v_pk_fma_f32 v[126:127], v[14:15], v[96:97], v[126:127]
	v_pk_fma_f32 v[128:129], v[6:7], v[96:97], v[128:129]
	v_pk_fma_f32 v[126:127], v[16:17], v[98:99], v[126:127]
	v_pk_fma_f32 v[128:129], v[8:9], v[98:99], v[128:129]
	v_pk_fma_f32 v[126:127], v[18:19], v[100:101], v[126:127]
	v_pk_fma_f32 v[128:129], v[10:11], v[100:101], v[128:129]
	ds_read_b128 v[94:97], v132 offset:768
	ds_read_b128 v[98:101], v132 offset:784
	v_add_f32_e32 v130, v126, v127
	v_add_f32_e32 v131, v128, v129
	v_add_u32_e32 v132, 0x200, v132
	v_add_u32_e32 v133, 0x200, v133
	s_add_i32 s6, s6, 2
	v_add_u32_e32 v134, 0x5f00, v133
	s_cmp_lt_i32 s6, s5
	s_cbranch_scc1 .Lscan4_loop
	s_nop 1
	v_add_f32_dpp v130, v130, v130 quad_perm:[1,0,3,2] row_mask:0xf bank_mask:0xf bound_ctrl:1
	v_add_f32_dpp v131, v131, v131 quad_perm:[1,0,3,2] row_mask:0xf bank_mask:0xf bound_ctrl:1
	s_nop 1
	v_add_f32_dpp v130, v130, v130 quad_perm:[2,3,0,1] row_mask:0xf bank_mask:0xf bound_ctrl:1
	v_add_f32_dpp v131, v131, v131 quad_perm:[2,3,0,1] row_mask:0xf bank_mask:0xf bound_ctrl:1
	s_nop 1
	v_add_f32_dpp v130, v130, v130 row_half_mirror row_mask:0xf bank_mask:0xf bound_ctrl:1
	v_add_f32_dpp v131, v131, v131 row_half_mirror row_mask:0xf bank_mask:0xf bound_ctrl:1
	s_nop 0
	ds_write_b64 v134, v[130:131]
	s_branch .LBB0_205

; __device__ __forceinline__ unsigned cvt_pk_bf16(float lo, float hi) { unsigned r; asm volatile("v_cvt_pk_bf16_f32 %0, %1, %2" : "=v"(r) : "v"(lo), "v"(hi)); return r; }
;     __device__ __forceinline__ void operator()(const f32x4 (&acc)[2][2][4][2], const pg8::Unit& u, int wr, int wc, int fr, int fq) const {
;         const int row0 = u.pm * 256 + wr * 64 + fr, col0 = u.pn * 128 + wc * 32 + 8 * fq;
; #pragma unroll
;         for (int ai = 0; ai < 2; ++ai)
; #pragma unroll
;             for (int m = 0; m < 4; ++m) { bf16_t* rowp = H + (size_t)(row0 + ai * 128 + m * 16) * DFF + col0;
;                 float hv[8];
; #pragma unroll
;                 for (int n = 0; n < 2; ++n)
; #pragma unroll
;                     for (int j = 0; j < 4; ++j) { const float g = acc[ai][0][m][n][j], up = acc[ai][1][m][n][j];
;                         hv[n * 4 + j] = g * __builtin_amdgcn_rcpf(1.0f + __builtin_amdgcn_exp2f(-g * LOG2E)) * up; }
;                 u32x4 w; w.x = cvt_pk_bf16(hv[0], hv[1]); w.y = cvt_pk_bf16(hv[2], hv[3]); w.z = cvt_pk_bf16(hv[4], hv[5]); w.w = cvt_pk_bf16(hv[6], hv[7]);
;                 __builtin_nontemporal_store(w, (u32x4*)rowp); }
;     }
.LBB0_701:
	v_mul_f32_e32 v146, 0xbfb8aa3b, v126
	v_exp_f32_e32 v146, v146
	v_lshl_or_b32 v162, s19, 7, v144
	v_lshl_add_u32 v161, s18, 8, v142
	v_ashrrev_i32_e32 v163, 31, v162
	v_add_f32_e32 v146, 1.0, v146
	v_rcp_f32_e32 v146, v146
	v_mov_b64_e32 v[140:141], s[2:3]
	v_mad_i64_i32 v[164:165], s[18:19], v161, s33, v[140:141]
	v_mul_f32_e32 v126, v126, v146
	v_mul_f32_e32 v122, v126, v122
	v_mul_f32_e32 v126, 0xbfb8aa3b, v127
	v_exp_f32_e32 v126, v126
	s_andn2_b64 vcc, exec, s[4:5]
	v_add_f32_e32 v126, 1.0, v126
	v_rcp_f32_e32 v126, v126
	s_nop 0
	v_mul_f32_e32 v126, v127, v126
	v_mul_f32_e32 v123, v126, v123
	v_mul_f32_e32 v126, 0xbfb8aa3b, v128
	v_exp_f32_e32 v126, v126
	s_nop 0
	v_add_f32_e32 v126, 1.0, v126
	v_rcp_f32_e32 v126, v126
	s_nop 0
	v_mul_f32_e32 v126, v128, v126
	v_mul_f32_e32 v124, v126, v124
	v_mul_f32_e32 v126, 0xbfb8aa3b, v129
	v_exp_f32_e32 v126, v126
	s_nop 0
	v_add_f32_e32 v126, 1.0, v126
	v_rcp_f32_e32 v126, v126
	s_nop 0
	v_mul_f32_e32 v126, v129, v126
	v_mul_f32_e32 v125, v126, v125
	v_mul_f32_e32 v126, 0xbfb8aa3b, v118
	v_exp_f32_e32 v126, v126
	s_nop 0
	v_add_f32_e32 v126, 1.0, v126
	v_rcp_f32_e32 v126, v126
	s_nop 0
	v_mul_f32_e32 v118, v118, v126
	v_mul_f32_e32 v118, v118, v114
	v_mul_f32_e32 v114, 0xbfb8aa3b, v119
	v_exp_f32_e32 v114, v114
	s_nop 0
	v_add_f32_e32 v114, 1.0, v114
	v_rcp_f32_e32 v114, v114
	s_nop 0
	v_mul_f32_e32 v114, v119, v114
	v_mul_f32_e32 v119, v114, v115
	v_mul_f32_e32 v114, 0xbfb8aa3b, v120
	v_exp_f32_e32 v114, v114
	s_nop 0
	v_add_f32_e32 v114, 1.0, v114
	v_rcp_f32_e32 v114, v114
	s_nop 0
	v_mul_f32_e32 v114, v120, v114
	v_mul_f32_e32 v126, v114, v116
	v_mul_f32_e32 v114, 0xbfb8aa3b, v121
	v_exp_f32_e32 v114, v114
	v_cvt_pk_bf16_f32 v116, v122, v123
	s_nop 0
	v_add_f32_e32 v114, 1.0, v114
	v_rcp_f32_e32 v114, v114
	s_nop 0
	v_mul_f32_e32 v114, v121, v114
	v_mul_f32_e32 v127, v114, v117
	v_lshlrev_b64 v[114:115], 1, v[162:163]
	v_lshl_add_u64 v[120:121], v[164:165], 0, v[114:115]
	v_cvt_pk_bf16_f32 v117, v124, v125
	v_cvt_pk_bf16_f32 v118, v118, v119
	v_cvt_pk_bf16_f32 v119, v126, v127
	global_store_dwordx4 v[120:121], v[116:119], off nt
	s_nop 1
	v_mul_f32_e32 v118, 0xbfb8aa3b, v110
	v_exp_f32_e32 v118, v118
	v_or_b32_e32 v116, 16, v161
	v_mad_i64_i32 v[116:117], s[18:19], v116, s33, v[140:141]
	v_add_f32_e32 v118, 1.0, v118
	v_rcp_f32_e32 v118, v118
	s_nop 0
	v_mul_f32_e32 v110, v110, v118
	v_mul_f32_e32 v106, v110, v106
	v_mul_f32_e32 v110, 0xbfb8aa3b, v111
	v_exp_f32_e32 v110, v110
	s_nop 0
	v_add_f32_e32 v110, 1.0, v110
	v_rcp_f32_e32 v110, v110
	s_nop 0
	v_mul_f32_e32 v110, v111, v110
	v_mul_f32_e32 v107, v110, v107
	v_mul_f32_e32 v110, 0xbfb8aa3b, v112
	v_exp_f32_e32 v110, v110
	s_nop 0
	v_add_f32_e32 v110, 1.0, v110
	v_rcp_f32_e32 v110, v110
	s_nop 0
	v_mul_f32_e32 v110, v112, v110
	v_mul_f32_e32 v108, v110, v108
	v_mul_f32_e32 v110, 0xbfb8aa3b, v113
	v_exp_f32_e32 v110, v110
	s_nop 0
	v_add_f32_e32 v110, 1.0, v110
	v_rcp_f32_e32 v110, v110
	s_nop 0
	v_mul_f32_e32 v110, v113, v110
	v_mul_f32_e32 v109, v110, v109
	v_mul_f32_e32 v110, 0xbfb8aa3b, v102
	v_exp_f32_e32 v110, v110
	s_nop 0
	v_add_f32_e32 v110, 1.0, v110
	v_rcp_f32_e32 v110, v110
	s_nop 0
	v_mul_f32_e32 v102, v102, v110
	v_mul_f32_e32 v110, v102, v98
	v_mul_f32_e32 v98, 0xbfb8aa3b, v103
	v_exp_f32_e32 v98, v98
	s_nop 0
	v_add_f32_e32 v98, 1.0, v98
	v_rcp_f32_e32 v98, v98
	s_nop 0
	v_mul_f32_e32 v98, v103, v98
	v_mul_f32_e32 v111, v98, v99
	v_mul_f32_e32 v98, 0xbfb8aa3b, v104
	v_exp_f32_e32 v98, v98
	v_lshl_add_u64 v[102:103], v[116:117], 0, v[114:115]
	v_add_f32_e32 v98, 1.0, v98
	v_rcp_f32_e32 v98, v98
	s_nop 0
	v_mul_f32_e32 v98, v104, v98
	v_mul_f32_e32 v104, v98, v100
	v_mul_f32_e32 v98, 0xbfb8aa3b, v105
	v_exp_f32_e32 v98, v98
	s_nop 0
	v_add_f32_e32 v98, 1.0, v98
	v_rcp_f32_e32 v98, v98
	s_nop 0
	v_mul_f32_e32 v98, v105, v98
	v_mul_f32_e32 v101, v98, v101
	v_cvt_pk_bf16_f32 v98, v106, v107
	v_cvt_pk_bf16_f32 v99, v108, v109
	v_cvt_pk_bf16_f32 v100, v110, v111
	v_cvt_pk_bf16_f32 v101, v104, v101
	global_store_dwordx4 v[102:103], v[98:101], off nt
	s_nop 1
	v_mul_f32_e32 v100, 0xbfb8aa3b, v94
	v_exp_f32_e32 v100, v100
	v_or_b32_e32 v98, 32, v161
	v_mad_i64_i32 v[98:99], s[18:19], v98, s33, v[140:141]
	v_add_f32_e32 v100, 1.0, v100
	v_rcp_f32_e32 v100, v100
	s_nop 0
	v_mul_f32_e32 v94, v94, v100
	v_mul_f32_e32 v90, v94, v90
	v_mul_f32_e32 v94, 0xbfb8aa3b, v95
	v_exp_f32_e32 v94, v94
	s_nop 0
	v_add_f32_e32 v94, 1.0, v94
	v_rcp_f32_e32 v94, v94
	s_nop 0
	v_mul_f32_e32 v94, v95, v94
	v_mul_f32_e32 v91, v94, v91
	v_mul_f32_e32 v94, 0xbfb8aa3b, v96
	v_exp_f32_e32 v94, v94
	s_nop 0
	v_add_f32_e32 v94, 1.0, v94
	v_rcp_f32_e32 v94, v94
	s_nop 0
	v_mul_f32_e32 v94, v96, v94
	v_mul_f32_e32 v92, v94, v92
	v_mul_f32_e32 v94, 0xbfb8aa3b, v97
	v_exp_f32_e32 v94, v94
	s_nop 0
	v_add_f32_e32 v94, 1.0, v94
	v_rcp_f32_e32 v94, v94
	s_nop 0
	v_mul_f32_e32 v94, v97, v94
	v_mul_f32_e32 v93, v94, v93
	v_mul_f32_e32 v94, 0xbfb8aa3b, v86
	v_exp_f32_e32 v94, v94
	s_nop 0
	v_add_f32_e32 v94, 1.0, v94
	v_rcp_f32_e32 v94, v94
	s_nop 0
	v_mul_f32_e32 v86, v86, v94
	v_mul_f32_e32 v94, v86, v82
	v_mul_f32_e32 v82, 0xbfb8aa3b, v87
	v_exp_f32_e32 v82, v82
	s_nop 0
	v_add_f32_e32 v82, 1.0, v82
	v_rcp_f32_e32 v82, v82
	s_nop 0
	v_mul_f32_e32 v82, v87, v82
	v_mul_f32_e32 v95, v82, v83
	v_mul_f32_e32 v82, 0xbfb8aa3b, v88
	v_exp_f32_e32 v82, v82
	v_lshl_add_u64 v[86:87], v[98:99], 0, v[114:115]
	v_add_f32_e32 v82, 1.0, v82
	v_rcp_f32_e32 v82, v82
	s_nop 0
	v_mul_f32_e32 v82, v88, v82
	v_mul_f32_e32 v88, v82, v84
	v_mul_f32_e32 v82, 0xbfb8aa3b, v89
	v_exp_f32_e32 v82, v82
	s_nop 0
	v_add_f32_e32 v82, 1.0, v82
	v_rcp_f32_e32 v82, v82
	s_nop 0
; __device__ __forceinline__ unsigned cvt_pk_bf16(float lo, float hi) { unsigned r; asm volatile("v_cvt_pk_bf16_f32 %0, %1, %2" : "=v"(r) : "v"(lo), "v"(hi)); return r; }
;     __device__ __forceinline__ void operator()(const f32x4 (&acc)[2][2][4][2], const pg8::Unit& u, int wr, int wc, int fr, int fq) const {
;     ...
;                     for (int j = 0; j < 4; ++j) { const float g = acc[ai][0][m][n][j], up = acc[ai][1][m][n][j];
;                         hv[n * 4 + j] = g * __builtin_amdgcn_rcpf(1.0f + __builtin_amdgcn_exp2f(-g * LOG2E)) * up; }
;                 u32x4 w; w.x = cvt_pk_bf16(hv[0], hv[1]); w.y = cvt_pk_bf16(hv[2], hv[3]); w.z = cvt_pk_bf16(hv[4], hv[5]); w.w = cvt_pk_bf16(hv[6], hv[7]);
;                 __builtin_nontemporal_store(w, (u32x4*)rowp); }
	v_mul_f32_e32 v82, v89, v82
	v_mul_f32_e32 v85, v82, v85
	v_cvt_pk_bf16_f32 v82, v90, v91
	v_cvt_pk_bf16_f32 v83, v92, v93
	v_cvt_pk_bf16_f32 v84, v94, v95
	v_cvt_pk_bf16_f32 v85, v88, v85
	global_store_dwordx4 v[86:87], v[82:85], off nt
	s_nop 1
	v_mul_f32_e32 v84, 0xbfb8aa3b, v78
	v_exp_f32_e32 v84, v84
	v_or_b32_e32 v82, 48, v161
	v_mad_i64_i32 v[82:83], s[18:19], v82, s33, v[140:141]
	v_add_f32_e32 v84, 1.0, v84
	v_rcp_f32_e32 v84, v84
	s_nop 0
	v_mul_f32_e32 v78, v78, v84
	v_mul_f32_e32 v74, v78, v74
	v_mul_f32_e32 v78, 0xbfb8aa3b, v79
	v_exp_f32_e32 v78, v78
	s_nop 0
	v_add_f32_e32 v78, 1.0, v78
	v_rcp_f32_e32 v78, v78
	s_nop 0
	v_mul_f32_e32 v78, v79, v78
	v_mul_f32_e32 v75, v78, v75
	v_mul_f32_e32 v78, 0xbfb8aa3b, v80
	v_exp_f32_e32 v78, v78
	s_nop 0
	v_add_f32_e32 v78, 1.0, v78
	v_rcp_f32_e32 v78, v78
	s_nop 0
	v_mul_f32_e32 v78, v80, v78
	v_mul_f32_e32 v76, v78, v76
	v_mul_f32_e32 v78, 0xbfb8aa3b, v81
	v_exp_f32_e32 v78, v78
	s_nop 0
	v_add_f32_e32 v78, 1.0, v78
	v_rcp_f32_e32 v78, v78
	s_nop 0
	v_mul_f32_e32 v78, v81, v78
	v_mul_f32_e32 v77, v78, v77
	v_mul_f32_e32 v78, 0xbfb8aa3b, v70
	v_exp_f32_e32 v78, v78
	s_nop 0
	v_add_f32_e32 v78, 1.0, v78
	v_rcp_f32_e32 v78, v78
	s_nop 0
	v_mul_f32_e32 v70, v70, v78
	v_mul_f32_e32 v78, v70, v66
	v_mul_f32_e32 v66, 0xbfb8aa3b, v71
	v_exp_f32_e32 v66, v66
	s_nop 0
	v_add_f32_e32 v66, 1.0, v66
	v_rcp_f32_e32 v66, v66
	s_nop 0
	v_mul_f32_e32 v66, v71, v66
	v_mul_f32_e32 v79, v66, v67
	v_mul_f32_e32 v66, 0xbfb8aa3b, v72
	v_exp_f32_e32 v66, v66
	v_lshl_add_u64 v[70:71], v[82:83], 0, v[114:115]
	v_add_f32_e32 v66, 1.0, v66
	v_rcp_f32_e32 v66, v66
	s_nop 0
	v_mul_f32_e32 v66, v72, v66
	v_mul_f32_e32 v72, v66, v68
	v_mul_f32_e32 v66, 0xbfb8aa3b, v73
	v_exp_f32_e32 v66, v66
	s_nop 0
	v_add_f32_e32 v66, 1.0, v66
	v_rcp_f32_e32 v66, v66
	s_nop 0
	v_mul_f32_e32 v66, v73, v66
	v_mul_f32_e32 v69, v66, v69
	v_cvt_pk_bf16_f32 v66, v74, v75
	v_cvt_pk_bf16_f32 v67, v76, v77
	v_cvt_pk_bf16_f32 v68, v78, v79
	v_cvt_pk_bf16_f32 v69, v72, v69
	global_store_dwordx4 v[70:71], v[66:69], off nt
	s_nop 1
	v_mul_f32_e32 v68, 0xbfb8aa3b, v62
	v_exp_f32_e32 v68, v68
	v_add_u32_e32 v66, 0x80, v161
	v_mad_i64_i32 v[66:67], s[18:19], v66, s33, v[140:141]
	v_add_f32_e32 v68, 1.0, v68
	v_rcp_f32_e32 v68, v68
	s_nop 0
	v_mul_f32_e32 v62, v62, v68
	v_mul_f32_e32 v58, v62, v58
	v_mul_f32_e32 v62, 0xbfb8aa3b, v63
	v_exp_f32_e32 v62, v62
	s_nop 0
	v_add_f32_e32 v62, 1.0, v62
	v_rcp_f32_e32 v62, v62
	s_nop 0
	v_mul_f32_e32 v62, v63, v62
	v_mul_f32_e32 v59, v62, v59
	v_mul_f32_e32 v62, 0xbfb8aa3b, v64
	v_exp_f32_e32 v62, v62
	s_nop 0
	v_add_f32_e32 v62, 1.0, v62
	v_rcp_f32_e32 v62, v62
	s_nop 0
	v_mul_f32_e32 v62, v64, v62
	v_mul_f32_e32 v60, v62, v60
	v_mul_f32_e32 v62, 0xbfb8aa3b, v65
	v_exp_f32_e32 v62, v62
	s_nop 0
	v_add_f32_e32 v62, 1.0, v62
	v_rcp_f32_e32 v62, v62
	s_nop 0
	v_mul_f32_e32 v62, v65, v62
	v_mul_f32_e32 v61, v62, v61
	v_mul_f32_e32 v62, 0xbfb8aa3b, v54
	v_exp_f32_e32 v62, v62
	s_nop 0
	v_add_f32_e32 v62, 1.0, v62
	v_rcp_f32_e32 v62, v62
	s_nop 0
	v_mul_f32_e32 v54, v54, v62
	v_mul_f32_e32 v62, v54, v50
	v_mul_f32_e32 v50, 0xbfb8aa3b, v55
	v_exp_f32_e32 v50, v50
	s_nop 0
	v_add_f32_e32 v50, 1.0, v50
	v_rcp_f32_e32 v50, v50
	s_nop 0
	v_mul_f32_e32 v50, v55, v50
	v_mul_f32_e32 v63, v50, v51
	v_mul_f32_e32 v50, 0xbfb8aa3b, v56
	v_exp_f32_e32 v50, v50
	v_lshl_add_u64 v[54:55], v[66:67], 0, v[114:115]
	v_add_f32_e32 v50, 1.0, v50
	v_rcp_f32_e32 v50, v50
	s_nop 0
	v_mul_f32_e32 v50, v56, v50
	v_mul_f32_e32 v56, v50, v52
	v_mul_f32_e32 v50, 0xbfb8aa3b, v57
	v_exp_f32_e32 v50, v50
	s_nop 0
	v_add_f32_e32 v50, 1.0, v50
	v_rcp_f32_e32 v50, v50
	s_nop 0
	v_mul_f32_e32 v50, v57, v50
	v_mul_f32_e32 v53, v50, v53
	v_cvt_pk_bf16_f32 v50, v58, v59
	v_cvt_pk_bf16_f32 v51, v60, v61
	v_cvt_pk_bf16_f32 v52, v62, v63
	v_cvt_pk_bf16_f32 v53, v56, v53
	global_store_dwordx4 v[54:55], v[50:53], off nt
	s_nop 1
	v_mul_f32_e32 v52, 0xbfb8aa3b, v46
	v_exp_f32_e32 v52, v52
	v_add_u32_e32 v50, 0x90, v161
	v_mad_i64_i32 v[50:51], s[18:19], v50, s33, v[140:141]
	v_add_f32_e32 v52, 1.0, v52
	v_rcp_f32_e32 v52, v52
	s_nop 0
	v_mul_f32_e32 v46, v46, v52
	v_mul_f32_e32 v42, v46, v42
	v_mul_f32_e32 v46, 0xbfb8aa3b, v47
	v_exp_f32_e32 v46, v46
	s_nop 0
	v_add_f32_e32 v46, 1.0, v46
	v_rcp_f32_e32 v46, v46
	s_nop 0
	v_mul_f32_e32 v46, v47, v46
	v_mul_f32_e32 v43, v46, v43
	v_mul_f32_e32 v46, 0xbfb8aa3b, v48
	v_exp_f32_e32 v46, v46
	s_nop 0
	v_add_f32_e32 v46, 1.0, v46
	v_rcp_f32_e32 v46, v46
	s_nop 0
	v_mul_f32_e32 v46, v48, v46
	v_mul_f32_e32 v44, v46, v44
	v_mul_f32_e32 v46, 0xbfb8aa3b, v49
	v_exp_f32_e32 v46, v46
	s_nop 0
	v_add_f32_e32 v46, 1.0, v46
	v_rcp_f32_e32 v46, v46
	s_nop 0
	v_mul_f32_e32 v46, v49, v46
	v_mul_f32_e32 v45, v46, v45
; __device__ __forceinline__ unsigned cvt_pk_bf16(float lo, float hi) { unsigned r; asm volatile("v_cvt_pk_bf16_f32 %0, %1, %2" : "=v"(r) : "v"(lo), "v"(hi)); return r; }
;     __device__ __forceinline__ void operator()(const f32x4 (&acc)[2][2][4][2], const pg8::Unit& u, int wr, int wc, int fr, int fq) const {
;     ...
;                     for (int j = 0; j < 4; ++j) { const float g = acc[ai][0][m][n][j], up = acc[ai][1][m][n][j];
;                         hv[n * 4 + j] = g * __builtin_amdgcn_rcpf(1.0f + __builtin_amdgcn_exp2f(-g * LOG2E)) * up; }
;                 u32x4 w; w.x = cvt_pk_bf16(hv[0], hv[1]); w.y = cvt_pk_bf16(hv[2], hv[3]); w.z = cvt_pk_bf16(hv[4], hv[5]); w.w = cvt_pk_bf16(hv[6], hv[7]);
;                 __builtin_nontemporal_store(w, (u32x4*)rowp); }
;     }
	v_mul_f32_e32 v46, 0xbfb8aa3b, v38
	v_exp_f32_e32 v46, v46
	s_nop 0
	v_add_f32_e32 v46, 1.0, v46
	v_rcp_f32_e32 v46, v46
	s_nop 0
	v_mul_f32_e32 v38, v38, v46
	v_mul_f32_e32 v46, v38, v34
	v_mul_f32_e32 v34, 0xbfb8aa3b, v39
	v_exp_f32_e32 v34, v34
	s_nop 0
	v_add_f32_e32 v34, 1.0, v34
	v_rcp_f32_e32 v34, v34
	s_nop 0
	v_mul_f32_e32 v34, v39, v34
	v_mul_f32_e32 v47, v34, v35
	v_mul_f32_e32 v34, 0xbfb8aa3b, v40
	v_exp_f32_e32 v34, v34
	v_lshl_add_u64 v[38:39], v[50:51], 0, v[114:115]
	v_add_f32_e32 v34, 1.0, v34
	v_rcp_f32_e32 v34, v34
	s_nop 0
	v_mul_f32_e32 v34, v40, v34
	v_mul_f32_e32 v40, v34, v36
	v_mul_f32_e32 v34, 0xbfb8aa3b, v41
	v_exp_f32_e32 v34, v34
	s_nop 0
	v_add_f32_e32 v34, 1.0, v34
	v_rcp_f32_e32 v34, v34
	s_nop 0
	v_mul_f32_e32 v34, v41, v34
	v_mul_f32_e32 v37, v34, v37
	v_cvt_pk_bf16_f32 v34, v42, v43
	v_cvt_pk_bf16_f32 v35, v44, v45
	v_cvt_pk_bf16_f32 v36, v46, v47
	v_cvt_pk_bf16_f32 v37, v40, v37
	global_store_dwordx4 v[38:39], v[34:37], off nt
	s_nop 1
	v_mul_f32_e32 v36, 0xbfb8aa3b, v30
	v_exp_f32_e32 v36, v36
	v_add_u32_e32 v34, 0xa0, v161
	v_mad_i64_i32 v[34:35], s[18:19], v34, s33, v[140:141]
	v_add_f32_e32 v36, 1.0, v36
	v_rcp_f32_e32 v36, v36
	s_nop 0
	v_mul_f32_e32 v30, v30, v36
	v_mul_f32_e32 v26, v30, v26
	v_mul_f32_e32 v30, 0xbfb8aa3b, v31
	v_exp_f32_e32 v30, v30
	s_nop 0
	v_add_f32_e32 v30, 1.0, v30
	v_rcp_f32_e32 v30, v30
	s_nop 0
	v_mul_f32_e32 v30, v31, v30
	v_mul_f32_e32 v27, v30, v27
	v_mul_f32_e32 v30, 0xbfb8aa3b, v32
	v_exp_f32_e32 v30, v30
	s_nop 0
	v_add_f32_e32 v30, 1.0, v30
	v_rcp_f32_e32 v30, v30
	s_nop 0
	v_mul_f32_e32 v30, v32, v30
	v_mul_f32_e32 v28, v30, v28
	v_mul_f32_e32 v30, 0xbfb8aa3b, v33
	v_exp_f32_e32 v30, v30
	s_nop 0
	v_add_f32_e32 v30, 1.0, v30
	v_rcp_f32_e32 v30, v30
	s_nop 0
	v_mul_f32_e32 v30, v33, v30
	v_mul_f32_e32 v29, v30, v29
	v_mul_f32_e32 v30, 0xbfb8aa3b, v22
	v_exp_f32_e32 v30, v30
	s_nop 0
	v_add_f32_e32 v30, 1.0, v30
	v_rcp_f32_e32 v30, v30
	s_nop 0
	v_mul_f32_e32 v22, v22, v30
	v_mul_f32_e32 v30, v22, v18
	v_mul_f32_e32 v18, 0xbfb8aa3b, v23
	v_exp_f32_e32 v18, v18
	s_nop 0
	v_add_f32_e32 v18, 1.0, v18
	v_rcp_f32_e32 v18, v18
	s_nop 0
	v_mul_f32_e32 v18, v23, v18
	v_mul_f32_e32 v31, v18, v19
	v_mul_f32_e32 v18, 0xbfb8aa3b, v24
	v_exp_f32_e32 v18, v18
	v_lshl_add_u64 v[22:23], v[34:35], 0, v[114:115]
	v_add_f32_e32 v18, 1.0, v18
	v_rcp_f32_e32 v18, v18
	s_nop 0
	v_mul_f32_e32 v18, v24, v18
	v_mul_f32_e32 v24, v18, v20
	v_mul_f32_e32 v18, 0xbfb8aa3b, v25
	v_exp_f32_e32 v18, v18
	s_nop 0
	v_add_f32_e32 v18, 1.0, v18
	v_rcp_f32_e32 v18, v18
	s_nop 0
	v_mul_f32_e32 v18, v25, v18
	v_mul_f32_e32 v21, v18, v21
	v_cvt_pk_bf16_f32 v18, v26, v27
	v_cvt_pk_bf16_f32 v19, v28, v29
	v_cvt_pk_bf16_f32 v20, v30, v31
	v_cvt_pk_bf16_f32 v21, v24, v21
	global_store_dwordx4 v[22:23], v[18:21], off nt
	s_nop 1
	v_mul_f32_e32 v20, 0xbfb8aa3b, v14
	v_exp_f32_e32 v20, v20
	v_add_u32_e32 v18, 0xb0, v161
	v_mad_i64_i32 v[18:19], s[18:19], v18, s33, v[140:141]
	v_add_f32_e32 v20, 1.0, v20
	v_rcp_f32_e32 v20, v20
	s_mov_b64 s[18:19], -1
	v_mul_f32_e32 v14, v14, v20
	v_mul_f32_e32 v10, v14, v10
	v_mul_f32_e32 v14, 0xbfb8aa3b, v15
	v_exp_f32_e32 v14, v14
	s_nop 0
	v_add_f32_e32 v14, 1.0, v14
	v_rcp_f32_e32 v14, v14
	s_nop 0
	v_mul_f32_e32 v14, v15, v14
	v_mul_f32_e32 v11, v14, v11
	v_mul_f32_e32 v14, 0xbfb8aa3b, v16
	v_exp_f32_e32 v14, v14
	s_nop 0
	v_add_f32_e32 v14, 1.0, v14
	v_rcp_f32_e32 v14, v14
	s_nop 0
	v_mul_f32_e32 v14, v16, v14
	v_mul_f32_e32 v12, v14, v12
	v_mul_f32_e32 v14, 0xbfb8aa3b, v17
	v_exp_f32_e32 v14, v14
	s_nop 0
	v_add_f32_e32 v14, 1.0, v14
	v_rcp_f32_e32 v14, v14
	s_nop 0
	v_mul_f32_e32 v14, v17, v14
	v_mul_f32_e32 v13, v14, v13
	v_mul_f32_e32 v14, 0xbfb8aa3b, v6
	v_exp_f32_e32 v14, v14
	s_nop 0
	v_add_f32_e32 v14, 1.0, v14
	v_rcp_f32_e32 v14, v14
	s_nop 0
	v_mul_f32_e32 v6, v6, v14
	v_mul_f32_e32 v14, v6, v2
	v_mul_f32_e32 v2, 0xbfb8aa3b, v7
	v_exp_f32_e32 v2, v2
	s_nop 0
	v_add_f32_e32 v2, 1.0, v2
	v_rcp_f32_e32 v2, v2
	s_nop 0
	v_mul_f32_e32 v2, v7, v2
	v_mul_f32_e32 v15, v2, v3
	v_mul_f32_e32 v2, 0xbfb8aa3b, v8
	v_exp_f32_e32 v2, v2
	v_lshl_add_u64 v[6:7], v[18:19], 0, v[114:115]
	v_add_f32_e32 v2, 1.0, v2
	v_rcp_f32_e32 v2, v2
	s_nop 0
	v_mul_f32_e32 v2, v8, v2
	v_mul_f32_e32 v8, v2, v4
	v_mul_f32_e32 v2, 0xbfb8aa3b, v9
	v_exp_f32_e32 v2, v2
	s_nop 0
	v_add_f32_e32 v2, 1.0, v2
	v_rcp_f32_e32 v2, v2
	s_nop 0
	v_mul_f32_e32 v2, v9, v2
	v_mul_f32_e32 v5, v2, v5
	v_cvt_pk_bf16_f32 v2, v10, v11
	v_cvt_pk_bf16_f32 v3, v12, v13
	v_cvt_pk_bf16_f32 v4, v14, v15
	v_cvt_pk_bf16_f32 v5, v8, v5
	global_store_dwordx4 v[6:7], v[2:5], off nt
	s_cbranch_vccnz .LBB0_690
	s_andn2_b64 vcc, exec, s[0:1]
	s_cbranch_vccnz .LBB0_689
	s_barrier
	s_branch .LBB0_689
